# v57 plus the EPI2 epilogue SGPR-base addressing, the prep conv-load hoist and the adaLN 16-loads-in-flight edits stacked
# speedup vs baseline: 1.0413x; 1.0129x over previous
.LBB0_511:
	v_lshl_add_u64 v[18:19], v[60:61], 0, s[6:7]
	v_add_co_u32_e64 v36, s[0:1], s3, v18
	ds_read_b128 v[10:13], v63
	ds_read_b128 v[14:17], v63 offset:16
	ds_read_b128 v[2:5], v63 offset:32
	ds_read_b128 v[38:41], v63 offset:4096
	ds_read_b128 v[28:31], v63 offset:8192
	ds_read_b128 v[20:23], v63 offset:8208
	ds_read_b128 v[32:35], v63 offset:12288
	ds_read_b128 v[42:45], v63 offset:12304
	ds_read_b128 v[46:49], v63 offset:16384
	ds_read_b128 v[24:27], v63 offset:16400
	v_addc_co_u32_e64 v37, s[0:1], 0, v19, s[0:1]
	s_mov_b32 s0, 0xc000
	s_nop 0
	v_add_co_u32_e64 v64, s[0:1], s0, v18
	global_load_dword v62, v[18:19], off nt
	s_nop 0
	v_addc_co_u32_e64 v65, s[0:1], 0, v19, s[0:1]
	s_mov_b32 s0, 0x12000
	s_nop 0
	v_add_co_u32_e64 v66, s[0:1], s0, v18
	s_waitcnt lgkmcnt(0)
	v_mov_b32_e32 v80, v10
	v_addc_co_u32_e64 v67, s[0:1], 0, v19, s[0:1]
	s_mov_b32 s0, 0x18000
	s_nop 0
	v_add_co_u32_e64 v68, s[0:1], s0, v18
	v_mov_b32_e32 v81, v46
	s_nop 0
	v_addc_co_u32_e64 v69, s[0:1], 0, v19, s[0:1]
	s_mov_b32 s0, 0x1e000
	s_nop 0
	v_add_co_u32_e64 v70, s[0:1], s0, v18
	v_mov_b32_e32 v46, v11
	s_nop 0
	v_addc_co_u32_e64 v71, s[0:1], 0, v19, s[0:1]
	s_mov_b32 s0, 0x24000
	s_nop 0
	v_add_co_u32_e64 v72, s[0:1], s0, v18
	v_mov_b32_e32 v78, v32
	s_nop 0
	v_addc_co_u32_e64 v73, s[0:1], 0, v19, s[0:1]
	s_mov_b32 s0, 0x2a000
	s_nop 0
	v_add_co_u32_e64 v10, s[0:1], s0, v18
	v_mov_b32_e32 v79, v28
	s_nop 0
	v_addc_co_u32_e64 v11, s[0:1], 0, v19, s[0:1]
	global_load_dword v84, v[36:37], off nt
	s_nop 0
	global_load_dword v64, v[64:65], off nt
	s_nop 0
	global_load_dword v66, v[66:67], off nt
	s_nop 0
	global_load_dword v86, v[68:69], off nt
	global_load_dword v88, v[70:71], off nt
	global_load_dword v76, v[72:73], off nt
	global_load_dword v74, v[10:11], off nt
	s_mov_b64 s[100:101], 0x30000
	v_lshl_add_u64 v[116:117], v[18:19], 0, s[100:101]
	global_load_dword v100, v[116:117], off nt
	s_mov_b64 s[100:101], 0x36000
	v_lshl_add_u64 v[118:119], v[18:19], 0, s[100:101]
	global_load_dword v102, v[118:119], off nt
	s_mov_b64 s[100:101], 0x3c000
	v_lshl_add_u64 v[120:121], v[18:19], 0, s[100:101]
	global_load_dword v104, v[120:121], off nt
	s_mov_b64 s[100:101], 0x42000
	v_lshl_add_u64 v[122:123], v[18:19], 0, s[100:101]
	global_load_dword v106, v[122:123], off nt
	s_mov_b64 s[100:101], 0x48000
	v_lshl_add_u64 v[124:125], v[18:19], 0, s[100:101]
	global_load_dword v108, v[124:125], off nt
	s_mov_b64 s[100:101], 0x4e000
	v_lshl_add_u64 v[126:127], v[18:19], 0, s[100:101]
	global_load_dword v110, v[126:127], off nt
	s_mov_b64 s[100:101], 0x54000
	v_lshl_add_u64 v[128:129], v[18:19], 0, s[100:101]
	global_load_dword v112, v[128:129], off nt
	s_mov_b64 s[100:101], 0x5a000
	v_lshl_add_u64 v[90:91], v[18:19], 0, s[100:101]
	global_load_dword v114, v[90:91], off nt
	v_mov_b32_e32 v28, v33
	v_mov_b32_e32 v32, v34
	v_mov_b32_e32 v33, v30
	v_mov_b32_e32 v82, v12
	v_mov_b32_e32 v83, v48
	v_mov_b32_e32 v30, v35
	v_mov_b32_e32 v48, v13
	ds_read_b128 v[34:37], v63 offset:4112
	ds_read_b128 v[10:13], v63 offset:48
	s_add_u32 s6, s6, 0x60000
	s_addc_u32 s7, s7, 0
	s_cmp_eq_u32 s6, 0x600000
	s_waitcnt vmcnt(15)
	v_fmac_f32_e32 v55, v62, v38
	v_pk_fma_f32 v[8:9], v[62:63], v[78:79], v[8:9] op_sel_hi:[0,1,1]
	v_pk_fma_f32 v[6:7], v[62:63], v[80:81], v[6:7] op_sel_hi:[0,1,1]
	s_waitcnt vmcnt(14)
	v_fmac_f32_e32 v55, v84, v39
	v_pk_fma_f32 v[8:9], v[84:85], v[28:29], v[8:9] op_sel_hi:[0,1,1]
	v_pk_fma_f32 v[28:29], v[84:85], v[46:47], v[6:7] op_sel_hi:[0,1,1]
	s_waitcnt vmcnt(13)
	v_fmac_f32_e32 v55, v64, v40
	s_nop 0
	s_waitcnt vmcnt(12)
	v_fmac_f32_e32 v55, v66, v41
	v_pk_fma_f32 v[32:33], v[64:65], v[32:33], v[8:9] op_sel_hi:[0,1,1]
	v_pk_fma_f32 v[28:29], v[64:65], v[82:83], v[28:29] op_sel_hi:[0,1,1]
	v_pk_fma_f32 v[30:31], v[66:67], v[30:31], v[32:33] op_sel_hi:[0,1,1]
	s_nop 0
	s_nop 0
	v_pk_fma_f32 v[28:29], v[66:67], v[48:49], v[28:29] op_sel_hi:[0,1,1]
	s_nop 0
	s_nop 0
	ds_read_b128 v[6:9], v63 offset:4128
	s_nop 0
	s_nop 0
	s_waitcnt vmcnt(11) lgkmcnt(2)
	v_fmac_f32_e32 v55, v86, v34
	s_nop 0
	s_waitcnt vmcnt(10)
	v_fmac_f32_e32 v55, v88, v35
	s_nop 0
	s_nop 0
	s_nop 0
	v_mov_b32_e32 v18, v42
	v_mov_b32_e32 v19, v20
	v_mov_b32_e32 v38, v14
	v_mov_b32_e32 v39, v24
	v_mov_b32_e32 v20, v43
	v_mov_b32_e32 v24, v15
	v_pk_fma_f32 v[18:19], v[86:87], v[18:19], v[30:31] op_sel_hi:[0,1,1]
	v_pk_fma_f32 v[38:39], v[86:87], v[38:39], v[28:29] op_sel_hi:[0,1,1]
	v_mov_b32_e32 v32, v44
	v_mov_b32_e32 v33, v22
	v_mov_b32_e32 v42, v16
	v_mov_b32_e32 v43, v26
	v_pk_fma_f32 v[34:35], v[88:89], v[20:21], v[18:19] op_sel_hi:[0,1,1]
	v_pk_fma_f32 v[24:25], v[88:89], v[24:25], v[38:39] op_sel_hi:[0,1,1]
	v_mov_b32_e32 v22, v45
	v_mov_b32_e32 v26, v17
	ds_read_b128 v[14:17], v63 offset:8224
	ds_read_b128 v[28:31], v63 offset:12320
	ds_read_b128 v[18:21], v63 offset:16416
	s_waitcnt vmcnt(9)
	v_pk_fma_f32 v[40:41], v[76:77], v[32:33], v[34:35] op_sel_hi:[0,1,1]
	v_pk_fma_f32 v[24:25], v[76:77], v[42:43], v[24:25] op_sel_hi:[0,1,1]
	v_fmac_f32_e32 v55, v76, v36
	s_waitcnt vmcnt(8)
	v_fmac_f32_e32 v55, v74, v37
	ds_read_b128 v[36:39], v63 offset:8240
	v_pk_fma_f32 v[44:45], v[74:75], v[22:23], v[40:41] op_sel_hi:[0,1,1]
	ds_read_b128 v[40:43], v63 offset:12336
	v_pk_fma_f32 v[26:27], v[74:75], v[26:27], v[24:25] op_sel_hi:[0,1,1]
	ds_read_b128 v[22:25], v63 offset:16432
	ds_read_b128 v[32:35], v63 offset:4144
	s_waitcnt lgkmcnt(5)
	v_mov_b32_e32 v74, v28
	v_mov_b32_e32 v75, v14
	v_mov_b32_e32 v14, v29
	v_mov_b32_e32 v28, v30
	v_mov_b32_e32 v29, v16
	v_mov_b32_e32 v16, v31
	v_mov_b32_e32 v30, v2
	s_waitcnt lgkmcnt(4)
	v_mov_b32_e32 v31, v18
	v_mov_b32_e32 v18, v3
	v_mov_b32_e32 v2, v4
	v_mov_b32_e32 v3, v20
	v_mov_b32_e32 v20, v5
	s_waitcnt lgkmcnt(2)
	v_mov_b32_e32 v4, v40
	v_mov_b32_e32 v5, v36
	v_mov_b32_e32 v36, v41
	v_mov_b32_e32 v40, v42
	v_mov_b32_e32 v41, v38
	v_mov_b32_e32 v38, v43
	v_mov_b32_e32 v42, v10
	s_waitcnt lgkmcnt(1)
	v_mov_b32_e32 v43, v22
	v_mov_b32_e32 v22, v11
	v_mov_b32_e32 v10, v12
	v_mov_b32_e32 v11, v24
	v_mov_b32_e32 v24, v13
	v_add_u32_e32 v63, 64, v63
	s_waitcnt vmcnt(7)
	v_fmac_f32_e32 v55, v100, v6
	v_pk_fma_f32 v[12:13], v[100:101], v[74:75], v[44:45] op_sel_hi:[0,1,1]
	v_pk_fma_f32 v[26:27], v[100:101], v[30:31], v[26:27] op_sel_hi:[0,1,1]
	s_waitcnt vmcnt(6)
	v_fmac_f32_e32 v55, v102, v7
	v_pk_fma_f32 v[6:7], v[102:103], v[14:15], v[12:13] op_sel_hi:[0,1,1]
	v_pk_fma_f32 v[12:13], v[102:103], v[18:19], v[26:27] op_sel_hi:[0,1,1]
	s_waitcnt vmcnt(5)
	v_fmac_f32_e32 v55, v104, v8
	v_pk_fma_f32 v[6:7], v[104:105], v[28:29], v[6:7] op_sel_hi:[0,1,1]
	v_pk_fma_f32 v[2:3], v[104:105], v[2:3], v[12:13] op_sel_hi:[0,1,1]
	s_waitcnt vmcnt(4)
	v_fmac_f32_e32 v55, v106, v9
	v_pk_fma_f32 v[6:7], v[106:107], v[16:17], v[6:7] op_sel_hi:[0,1,1]
	v_pk_fma_f32 v[2:3], v[106:107], v[20:21], v[2:3] op_sel_hi:[0,1,1]
	s_waitcnt vmcnt(3) lgkmcnt(0)
	v_fmac_f32_e32 v55, v108, v32
	v_pk_fma_f32 v[4:5], v[108:109], v[4:5], v[6:7] op_sel_hi:[0,1,1]
	v_pk_fma_f32 v[2:3], v[108:109], v[42:43], v[2:3] op_sel_hi:[0,1,1]
	s_waitcnt vmcnt(2)
	v_fmac_f32_e32 v55, v110, v33
	v_pk_fma_f32 v[4:5], v[110:111], v[36:37], v[4:5] op_sel_hi:[0,1,1]
	v_pk_fma_f32 v[2:3], v[110:111], v[22:23], v[2:3] op_sel_hi:[0,1,1]
	s_waitcnt vmcnt(1)
	v_fmac_f32_e32 v55, v112, v34
	v_pk_fma_f32 v[4:5], v[112:113], v[40:41], v[4:5] op_sel_hi:[0,1,1]
	v_pk_fma_f32 v[2:3], v[112:113], v[10:11], v[2:3] op_sel_hi:[0,1,1]
	s_waitcnt vmcnt(0)
	v_fmac_f32_e32 v55, v114, v35
	v_pk_fma_f32 v[8:9], v[114:115], v[38:39], v[4:5] op_sel_hi:[0,1,1]
	v_pk_fma_f32 v[6:7], v[114:115], v[24:25], v[2:3] op_sel_hi:[0,1,1]
	s_cbranch_scc0 .LBB0_511
	ds_write_b32 v54, v6 offset:20480
	ds_write2st64_b32 v53, v55, v9 offset0:81 offset1:82
	ds_write2st64_b32 v53, v8, v7 offset0:83 offset1:84
	s_waitcnt lgkmcnt(0)
	s_barrier
	s_and_saveexec_b64 s[0:1], vcc
	s_cbranch_execz .LBB0_509
	s_mul_i32 s6, s13, 0x1800
	s_add_i32 s6, s6, s4
	v_or_b32_e32 v2, s6, v50
	v_readlane_b32 s36, v254, 27
	v_ashrrev_i32_e32 v3, 31, v2
	v_readlane_b32 s38, v254, 29
	v_readlane_b32 s39, v254, 30
	s_mul_i32 s6, s13, 5
	s_add_i32 s7, s6, 2
	v_lshl_add_u64 v[2:3], v[2:3], 2, s[38:39]
	global_load_dword v32, v[2:3], off
	ds_read2st64_b32 v[4:5], v52 offset0:80 offset1:81
	ds_read2st64_b32 v[6:7], v52 offset0:84 offset1:85
	ds_read2st64_b32 v[8:9], v52 offset0:86 offset1:87
	ds_read2st64_b32 v[10:11], v52 offset0:82 offset1:83
	ds_read2st64_b32 v[12:13], v52 offset0:90 offset1:91
	ds_read2st64_b32 v[14:15], v52 offset0:94 offset1:95
	ds_read2st64_b32 v[16:17], v52 offset0:92 offset1:93
	ds_read2st64_b32 v[18:19], v52 offset0:88 offset1:89
	ds_read2st64_b32 v[20:21], v52 offset0:96 offset1:97
	ds_read2st64_b32 v[22:23], v52 offset0:98 offset1:99
	s_waitcnt lgkmcnt(8)
	v_add_f32_e32 v4, v4, v7
	v_lshl_add_u64 v[2:3], s[4:5], 2, v[56:57]
	s_waitcnt lgkmcnt(7)
	v_add_f32_e32 v5, v5, v8
	s_waitcnt lgkmcnt(6)
	v_add_f32_e32 v7, v10, v9
	s_waitcnt lgkmcnt(2)
	v_add_f32_e32 v8, v11, v18
	v_add_f32_e32 v6, v6, v19
	v_add_f32_e32 v4, v4, v12
	v_mad_i64_i32 v[24:25], s[4:5], s6, v204, v[2:3]
	v_add_f32_e32 v5, v5, v13
	v_add_f32_e32 v7, v7, v16
	v_add_f32_e32 v8, v8, v17
	v_add_f32_e32 v6, v6, v14
	v_add_f32_e32 v4, v4, v15
	s_add_i32 s4, s6, 1
	s_add_i32 s13, s6, 3
	s_add_i32 s6, s6, 4
	s_waitcnt lgkmcnt(1)
	v_add_f32_e32 v5, v5, v20
	v_add_f32_e32 v7, v7, v21
	s_waitcnt lgkmcnt(0)
	v_add_f32_e32 v8, v8, v22
	v_add_f32_e32 v6, v6, v23
	v_readlane_b32 s37, v254, 28
	v_readlane_b32 s40, v254, 31
	v_readlane_b32 s41, v254, 32
	v_readlane_b32 s42, v254, 33
	v_readlane_b32 s43, v254, 34
	v_readlane_b32 s44, v254, 35
	v_readlane_b32 s45, v254, 36
	v_readlane_b32 s46, v254, 37
	v_readlane_b32 s47, v254, 38
	v_readlane_b32 s48, v254, 39
	v_readlane_b32 s49, v254, 40
	v_readlane_b32 s50, v254, 41
	v_readlane_b32 s51, v254, 42
	v_mad_i64_i32 v[26:27], s[4:5], s4, v204, v[2:3]
	v_mad_i64_i32 v[28:29], s[4:5], s7, v204, v[2:3]
	v_mad_i64_i32 v[30:31], s[4:5], s13, v204, v[2:3]
	v_mad_i64_i32 v[2:3], s[4:5], s6, v204, v[2:3]
	s_waitcnt vmcnt(0)
	v_add_f32_e32 v4, v32, v4
	v_add_f32_e32 v5, v32, v5
	v_add_f32_e32 v7, v32, v7
	v_add_f32_e32 v8, v32, v8
	v_add_f32_e32 v6, v32, v6
	global_store_dword v[24:25], v4, off
	global_store_dword v[26:27], v5, off
	global_store_dword v[28:29], v7, off
	global_store_dword v[30:31], v8, off
	global_store_dword v[2:3], v6, off
	s_branch .LBB0_509
